# phase-2 tile sets reassigned: the workgroups that lose issue arbitration on their CU (bid >= 256, measured ~8 us slower for equal work) get the cheaper tile-type sets, the others the sets with K/V til
# speedup vs baseline: 1.0114x; 1.0061x over previous
.LBB0_232:
.LBB0_233:
	s_ashr_i32 s2, s76, 3
	s_and_b32 s0, s2, 31
	s_lshr_b32 s1, s2, 5
	s_xor_b32 s1, s1, 1
	s_lshl_b32 s1, s1, 3
	s_and_b32 s2, s0, 7
	s_or_b32 s2, s2, s1
	s_lshr_b32 s0, s0, 3
	s_lshl_b32 s0, s0, 4
	s_or_b32 s2, s2, s0
	s_cmpk_gt_i32 s2, 0xbf
	s_cbranch_scc1 .LBB0_311
	s_lshl_b32 s0, s76, 3
	s_and_b32 s24, s0, 56
	s_ashr_i32 s25, s42, 3
	s_add_u32 s6, s58, 0xcd1000
	s_addc_u32 s7, s59, 0
	s_add_u32 s8, s58, 0x2cd1000
	s_addc_u32 s9, s59, 0
	s_add_u32 s10, s58, 0x8cd1000
	s_addc_u32 s11, s59, 0
	s_add_u32 s28, s58, 0xbd0000
	v_mbcnt_lo_u32_b32 v0, -1, 0
	s_addc_u32 s29, s59, 0
	v_mov_b32_e32 v161, 0
	s_mov_b32 s33, 0x10000
	s_mov_b32 s31, 0
	s_mov_b32 s37, 0x20000
	s_mov_b32 s39, 0x30000
	s_mov_b32 s66, 0x40000
	s_mov_b32 s67, 0x50000
	s_mov_b32 s68, 0x60000
	s_mov_b32 s69, 0x70000
	s_movk_i32 s77, 0x3ff
	s_movk_i32 s78, 0x5ff
	s_movk_i32 s79, 0xfe00
	s_movk_i32 s80, 0x1800
	s_mov_b64 s[34:35], 0x80
	s_movk_i32 s81, 0x1ff
	s_mov_b32 s36, 0x3c800000
	s_mov_b32 s38, 0x358637bd
	s_mov_b32 s82, 0x800000
	v_mbcnt_hi_u32_b32 v186, -1, v0
	s_branch .LBB0_237
